# v015 plus HGRN chunk-state buffer K0 in WS_KK and no grid barrier after step 2
# baseline (speedup 1.0000x reference)
; #define LAS __attribute__((address_space(3)))
; __device__ __forceinline__ unsigned xb_add(unsigned* p, unsigned v) { return __hip_atomic_fetch_add(p, v, __ATOMIC_RELAXED, __HIP_MEMORY_SCOPE_AGENT); }
; __device__ __forceinline__ unsigned xb_xcc_id() { return (unsigned)__builtin_amdgcn_s_getreg((3 << 11) | 20) & 0xFu; }
; __device__ __forceinline__ XcdBarrier xcd_barrier_post(unsigned* bar, volatile LAS unsigned* st) {
;     XcdBarrier b; b.bar = bar; b.x = xb_xcc_id(); b.st = st;
;     if (threadIdx.x == 0) (void)xb_add(&bar[XB_XCNT(b.x)], 1u);
;     return b;
; __global__ void __launch_bounds__(512) fwd_kernel(Params p) {
;     ...
;     if (threadIdx.x < NSTEPS) {
;         GD g{}; const int fl = build_desc((int)threadIdx.x, p, g);
;         LAS unsigned* t = (LAS unsigned*)(lds + LDS_TAB) + threadIdx.x * TABW;
;         t[0] = (unsigned)fl; put64(t, 2, (unsigned long long)g.A0); put64(t, 4, (unsigned long long)g.B0); t[6] = g.lda; t[7] = g.ldb; t[8] = g.K; t[9] = g.nM; t[10] = g.nN; t[11] = g.nz; t[12] = g.nz2;
;         put64(t, 14, (unsigned long long)g.sA1); put64(t, 16, (unsigned long long)g.sA2); put64(t, 18, (unsigned long long)g.sB1); put64(t, 20, (unsigned long long)g.sB2); t[22] = g.mode; t[23] = g.c0;
;         put64(t, 24, (unsigned long long)g.o0); put64(t, 26, (unsigned long long)g.o1); put64(t, 28, (unsigned long long)g.o2); put64(t, 30, (unsigned long long)g.o3); put64(t, 32, (unsigned long long)g.o4);
;         put64(t, 34, (unsigned long long)g.f0); put64(t, 36, (unsigned long long)g.f1); t[38] = g.ldc; t[39] = g.ro1; t[40] = g.co2; t[41] = __float_as_uint(g.scale); t[42] = g.ro2; put64(t, 44, (unsigned long long)g.f2); t[46] = g.kstA; t[47] = g.kstB; put64(t, 48, (unsigned long long)g.pstA); put64(t, 50, (unsigned long long)g.pstB);
;     }
;     if (threadIdx.x < 4) ((LAS unsigned*)(lds + LDS_BARST))[threadIdx.x] = 0u;
;     __syncthreads();
;     (void)xcd_barrier_post((unsigned*)(p.ws + WS_BAR), (volatile LAS unsigned*)(lds + LDS_BARST));
.LBB0_64:
	s_or_b64 exec, exec, s[0:1]
	v_cmp_gt_u32_e32 vcc, 4, v201
	s_and_saveexec_b64 s[0:1], vcc
	v_lshl_add_u32 v1, v201, 2, 0
	v_add_u32_e32 v1, 0x23000, v1
	v_mov_b32_e32 v2, 0
	ds_write_b32 v1, v2
	v_mov_b32_e32 v2, 0x80
	v_mov_b32_e32 v1, 0x21a5c
	ds_write_b32 v1, v2
	ds_write_b32 v1, v2 offset:512
	v_mov_b32_e32 v2, 0
	v_mov_b32_e32 v1, 0x21200
	ds_write_b32 v1, v2
	v_mov_b32_e32 v2, 24
	v_mov_b32_e32 v1, 0x22128
	ds_write_b32 v1, v2
	s_or_b64 exec, exec, s[0:1]
	s_waitcnt lgkmcnt(0)
	s_barrier
	s_getreg_b32 s4, hwreg(HW_REG_XCC_ID, 0, 4)
	s_mov_b32 s39, 0
	v_cmp_eq_u32_e32 vcc, 0, v201
	s_and_saveexec_b64 s[0:1], vcc
	s_cbranch_execz .LBB0_69
	s_mov_b64 s[2:3], exec
	v_mbcnt_lo_u32_b32 v1, s2, 0
	v_mbcnt_hi_u32_b32 v1, s3, v1
	v_cmp_eq_u32_e32 vcc, 0, v1
	s_and_b64 s[6:7], exec, vcc
	s_mov_b64 exec, s[6:7]
	s_cbranch_execz .LBB0_69
	s_lshl_b32 s4, s4, 8
	s_and_b32 s4, s4, 0xf00
	s_add_u32 s4, s10, s4
	s_addc_u32 s5, s11, 0
	s_bcnt1_i32_b64 s2, s[2:3]
	v_mov_b32_e32 v1, 0x10000
	v_mov_b32_e32 v2, s2
	global_atomic_add v1, v2, s[4:5] offset:1024
